# NSA selected groups: all 8 K fragment LDS reads issued up front (deeper prefetch, counted lgkmcnt ladder) instead of one step ahead
# speedup vs baseline: 1.0050x; 1.0036x over previous
; #define LAS __attribute__((address_space(3)))
; #define MFMA16(a, b, c) __builtin_amdgcn_mfma_f32_16x16x32_bf16((a), (b), (c), 0, 0, 0)
; __device__ __forceinline__ void sel_group(const LAS bf16_t* Kt, const LAS bf16_t* Vt, LAS float* S, const bf16x8 qB0, const bf16x8 qB1, int jc, int rc, bool valid, bool masked, int tw64, int lr, int q) {
;     LAS float* Srow = S + (jc * 3 + rc) * 68;
;     const float mref = Srow[65]; const bool st = Srow[66] != 0.f;
;     f32x4 acc[4];
; #pragma unroll
;     for (int dt = 0; dt < 4; ++dt) acc[dt] = *(const LAS f32x4*)(Srow + 16 * dt + 4 * q);
;     float lc = Srow[64];
;     const float nm = valid ? -mref : -1e30f;
;     const f32x4 c0 = (f32x4){nm, nm, nm, nm};
;     const LAS bf16_t* kbase = Kt + lr * 72 + 8 * q;
;     f32x4 s[4];
;     {
;         bf16x8 kf[2][2];
;         kf[0][0] = *(const LAS bf16x8*)(kbase); kf[0][1] = *(const LAS bf16x8*)(kbase + 32);
; #pragma unroll
;         for (int mt = 0; mt < 4; ++mt) {
;             if (mt < 3) { kf[(mt + 1) & 1][0] = *(const LAS bf16x8*)(kbase + 16 * (mt + 1) * 72); kf[(mt + 1) & 1][1] = *(const LAS bf16x8*)(kbase + 16 * (mt + 1) * 72 + 32); }
;             __builtin_amdgcn_sched_barrier(0);
;             __builtin_amdgcn_s_setprio(1); s[mt] = MFMA16(kf[mt & 1][0], qB0, c0); s[mt] = MFMA16(kf[mt & 1][1], qB1, s[mt]); __builtin_amdgcn_s_setprio(0);
;             __builtin_amdgcn_sched_barrier(0);
;         }
;     }
;     if (masked) {
;         const int hq = tw64 + jc - 4 * q;
; #pragma unroll
;         for (int mt = 0; mt < 4; ++mt)
; #pragma unroll
;             for (int i = 0; i < 4; ++i) s[mt][i] = ((16 * mt + i) <= hq) ? s[mt][i] : -1e30f;
.Lsp_gdone_loop:
	s_waitcnt lgkmcnt(0)
	s_cmp_eq_u32 s101, 1
	s_cselect_b64 s[2:3], -1, 0
	s_cmp_eq_u32 s45, s38
	s_cselect_b64 s[12:13], -1, 0
	v_add_u32_e32 v48, s6, v99
	v_add_u32_e32 v117, v48, v97
	v_cndmask_b32_e64 v48, 0, 1, s[12:13]
	v_add3_u32 v115, s6, v104, v114
	s_cmp_eq_u32 s10, 0
	v_cmp_ne_u32_e64 s[72:73], 1, v48
	s_barrier
	s_cbranch_scc1 .LBB0_1078
	v_mad_u64_u32 v[48:49], s[4:5], v120, 3, v[88:89]
	v_mul_lo_u32 v48, v48, s36
	v_add_u32_e32 v119, s49, v48
	v_add_u32_e32 v48, v119, v97
	ds_read_b96 v[84:86], v119 offset:46336
	ds_read_b128 v[64:67], v117
	ds_read_b128 v[68:71], v117 offset:64
	ds_read_b128 v[72:75], v117 offset:2304
	ds_read_b128 v[122:125], v117 offset:2368
	ds_read_b128 v[130:133], v117 offset:4608
	ds_read_b128 v[134:137], v117 offset:4672
	ds_read_b128 v[174:177], v117 offset:6912
	ds_read_b128 v[138:141], v117 offset:6976
	ds_read_b128 v[60:63], v48 offset:46080
	ds_read_b128 v[56:59], v48 offset:46144
	ds_read_b128 v[52:55], v48 offset:46208
	ds_read_b128 v[48:51], v48 offset:46272
	s_waitcnt lgkmcnt(12)
	v_cndmask_b32_e64 v126, v222, -v85, s[76:77]
	v_mov_b32_e32 v127, v126
	v_mov_b32_e32 v128, v126
	v_mov_b32_e32 v129, v126
	s_setprio 1
	s_waitcnt lgkmcnt(11)
	v_mfma_f32_16x16x32_bf16 v[64:67], v[64:67], v[76:79], v[126:129]
	s_waitcnt lgkmcnt(10)
	v_mfma_f32_16x16x32_bf16 v[64:67], v[68:71], v[80:83], v[64:67]
	s_waitcnt lgkmcnt(9)
	v_mfma_f32_16x16x32_bf16 v[68:71], v[72:75], v[76:79], v[126:129]
	s_waitcnt lgkmcnt(8)
	v_mfma_f32_16x16x32_bf16 v[68:71], v[122:125], v[80:83], v[68:71]
	s_waitcnt lgkmcnt(7)
	v_mfma_f32_16x16x32_bf16 v[72:75], v[130:133], v[76:79], v[126:129]
	s_waitcnt lgkmcnt(6)
	v_mfma_f32_16x16x32_bf16 v[72:75], v[134:137], v[80:83], v[72:75]
	s_waitcnt lgkmcnt(5)
	v_mfma_f32_16x16x32_bf16 v[76:79], v[174:177], v[76:79], v[126:129]
	s_waitcnt lgkmcnt(4)
	v_mfma_f32_16x16x32_bf16 v[76:79], v[138:141], v[80:83], v[76:79]
	s_setprio 0
	s_and_b64 vcc, exec, s[72:73]
	s_cbranch_vccnz .LBB0_1067
	v_add_u32_e32 v80, v120, v111
	v_cmp_lt_i32_e32 vcc, -1, v80
	s_nop 1
	v_cndmask_b32_e32 v64, v222, v64, vcc
	v_cmp_lt_i32_e32 vcc, 0, v80
	s_nop 1
	v_cndmask_b32_e32 v65, v222, v65, vcc
	v_cmp_lt_i32_e32 vcc, 1, v80
	s_nop 1
	v_cndmask_b32_e32 v66, v222, v66, vcc
	v_cmp_lt_i32_e32 vcc, 2, v80
	s_nop 1
	v_cndmask_b32_e32 v67, v222, v67, vcc
	v_cmp_lt_i32_e32 vcc, 15, v80
	s_nop 1
	v_cndmask_b32_e32 v68, v222, v68, vcc
	v_cmp_lt_i32_e32 vcc, 16, v80
	s_nop 1
	v_cndmask_b32_e32 v69, v222, v69, vcc
	v_cmp_lt_i32_e32 vcc, 17, v80
	s_nop 1
	v_cndmask_b32_e32 v70, v222, v70, vcc
	v_cmp_lt_i32_e32 vcc, 18, v80
	s_nop 1
	v_cndmask_b32_e32 v71, v222, v71, vcc
	v_cmp_lt_i32_e32 vcc, 31, v80
	s_nop 1
	v_cndmask_b32_e32 v72, v222, v72, vcc
	v_cmp_lt_i32_e32 vcc, 32, v80
	s_nop 1
	v_cndmask_b32_e32 v73, v222, v73, vcc
	v_cmp_lt_i32_e32 vcc, 33, v80
	s_nop 1
	v_cndmask_b32_e32 v74, v222, v74, vcc
	v_cmp_lt_i32_e32 vcc, 34, v80
	s_nop 1
	v_cndmask_b32_e32 v75, v222, v75, vcc
	v_cmp_lt_i32_e32 vcc, 47, v80
	s_nop 1
	v_cndmask_b32_e32 v76, v222, v76, vcc
	v_cmp_lt_i32_e32 vcc, 48, v80
	s_nop 1
	v_cndmask_b32_e32 v77, v222, v77, vcc
	v_cmp_lt_i32_e32 vcc, 49, v80
	s_nop 1
	v_cndmask_b32_e32 v78, v222, v78, vcc
	v_cmp_lt_i32_e32 vcc, 50, v80
	s_nop 1
	v_cndmask_b32_e32 v79, v222, v79, vcc

; #define LAS __attribute__((address_space(3)))
; #define MFMA16(a, b, c) __builtin_amdgcn_mfma_f32_16x16x32_bf16((a), (b), (c), 0, 0, 0)
; __device__ __forceinline__ void sel_group(const LAS bf16_t* Kt, const LAS bf16_t* Vt, LAS float* S, const bf16x8 qB0, const bf16x8 qB1, int jc, int rc, bool valid, bool masked, int tw64, int lr, int q) {
;     LAS float* Srow = S + (jc * 3 + rc) * 68;
;     const float mref = Srow[65]; const bool st = Srow[66] != 0.f;
;     f32x4 acc[4];
; #pragma unroll
;     for (int dt = 0; dt < 4; ++dt) acc[dt] = *(const LAS f32x4*)(Srow + 16 * dt + 4 * q);
;     float lc = Srow[64];
;     const float nm = valid ? -mref : -1e30f;
;     const f32x4 c0 = (f32x4){nm, nm, nm, nm};
;     const LAS bf16_t* kbase = Kt + lr * 72 + 8 * q;
;     f32x4 s[4];
;     {
;         bf16x8 kf[2][2];
;         kf[0][0] = *(const LAS bf16x8*)(kbase); kf[0][1] = *(const LAS bf16x8*)(kbase + 32);
; #pragma unroll
;         for (int mt = 0; mt < 4; ++mt) {
;             if (mt < 3) { kf[(mt + 1) & 1][0] = *(const LAS bf16x8*)(kbase + 16 * (mt + 1) * 72); kf[(mt + 1) & 1][1] = *(const LAS bf16x8*)(kbase + 16 * (mt + 1) * 72 + 32); }
;             __builtin_amdgcn_sched_barrier(0);
;             __builtin_amdgcn_s_setprio(1); s[mt] = MFMA16(kf[mt & 1][0], qB0, c0); s[mt] = MFMA16(kf[mt & 1][1], qB1, s[mt]); __builtin_amdgcn_s_setprio(0);
;             __builtin_amdgcn_sched_barrier(0);
;         }
;     }
;     if (masked) {
;         const int hq = tw64 + jc - 4 * q;
; #pragma unroll
;         for (int mt = 0; mt < 4; ++mt)
; #pragma unroll
;             for (int i = 0; i < 4; ++i) s[mt][i] = ((16 * mt + i) <= hq) ? s[mt][i] : -1e30f;
.LBB0_1078:
	s_cmp_lt_u32 s10, 6
	s_cbranch_scc1 .LBB0_1092
	v_mad_u64_u32 v[48:49], s[4:5], v118, 3, v[92:93]
	v_mul_lo_u32 v48, v48, s36
	v_add_u32_e32 v79, s49, v48
	v_add_u32_e32 v48, v79, v97
	ds_read_b96 v[76:78], v79 offset:46336
	ds_read_b128 v[64:67], v117
	ds_read_b128 v[68:71], v117 offset:64
	ds_read_b128 v[72:75], v117 offset:2304
	ds_read_b128 v[80:83], v117 offset:2368
	ds_read_b128 v[124:127], v117 offset:4608
	ds_read_b128 v[128:131], v117 offset:4672
	ds_read_b128 v[174:177], v117 offset:6912
	ds_read_b128 v[132:135], v117 offset:6976
	ds_read_b128 v[60:63], v48 offset:46080
	ds_read_b128 v[56:59], v48 offset:46144
	ds_read_b128 v[52:55], v48 offset:46208
	ds_read_b128 v[48:51], v48 offset:46272
	s_waitcnt lgkmcnt(12)
	v_cndmask_b32_e64 v120, v222, -v77, s[74:75]
	v_mov_b32_e32 v121, v120
	v_mov_b32_e32 v122, v120
	v_mov_b32_e32 v123, v120
	s_setprio 1
	s_waitcnt lgkmcnt(11)
	v_mfma_f32_16x16x32_bf16 v[64:67], v[64:67], v[40:43], v[120:123]
	s_waitcnt lgkmcnt(10)
	v_mfma_f32_16x16x32_bf16 v[64:67], v[68:71], v[44:47], v[64:67]
	s_waitcnt lgkmcnt(9)
	v_mfma_f32_16x16x32_bf16 v[68:71], v[72:75], v[40:43], v[120:123]
	s_waitcnt lgkmcnt(8)
	v_mfma_f32_16x16x32_bf16 v[68:71], v[80:83], v[44:47], v[68:71]
	s_waitcnt lgkmcnt(7)
	v_mfma_f32_16x16x32_bf16 v[72:75], v[124:127], v[40:43], v[120:123]
	s_waitcnt lgkmcnt(6)
	v_mfma_f32_16x16x32_bf16 v[72:75], v[128:131], v[44:47], v[72:75]
	s_waitcnt lgkmcnt(5)
	v_mfma_f32_16x16x32_bf16 v[40:43], v[174:177], v[40:43], v[120:123]
	s_waitcnt lgkmcnt(4)
	v_mfma_f32_16x16x32_bf16 v[40:43], v[132:135], v[44:47], v[40:43]
	s_setprio 0
	s_and_b64 vcc, exec, s[72:73]
	s_cbranch_vccnz .LBB0_1081
	v_add_u32_e32 v44, v118, v111
	v_cmp_lt_i32_e32 vcc, -1, v44
	s_nop 1
	v_cndmask_b32_e32 v64, v222, v64, vcc
	v_cmp_lt_i32_e32 vcc, 0, v44
	s_nop 1
	v_cndmask_b32_e32 v65, v222, v65, vcc
	v_cmp_lt_i32_e32 vcc, 1, v44
	s_nop 1
	v_cndmask_b32_e32 v66, v222, v66, vcc
	v_cmp_lt_i32_e32 vcc, 2, v44
	s_nop 1
	v_cndmask_b32_e32 v67, v222, v67, vcc
	v_cmp_lt_i32_e32 vcc, 15, v44
	s_nop 1
	v_cndmask_b32_e32 v68, v222, v68, vcc
	v_cmp_lt_i32_e32 vcc, 16, v44
	s_nop 1
	v_cndmask_b32_e32 v69, v222, v69, vcc
	v_cmp_lt_i32_e32 vcc, 17, v44
	s_nop 1
	v_cndmask_b32_e32 v70, v222, v70, vcc
	v_cmp_lt_i32_e32 vcc, 18, v44
	s_nop 1
	v_cndmask_b32_e32 v71, v222, v71, vcc
	v_cmp_lt_i32_e32 vcc, 31, v44
	s_nop 1
	v_cndmask_b32_e32 v72, v222, v72, vcc
	v_cmp_lt_i32_e32 vcc, 32, v44
	s_nop 1
	v_cndmask_b32_e32 v73, v222, v73, vcc
	v_cmp_lt_i32_e32 vcc, 33, v44
	s_nop 1
	v_cndmask_b32_e32 v74, v222, v74, vcc
	v_cmp_lt_i32_e32 vcc, 34, v44
	s_nop 1
	v_cndmask_b32_e32 v75, v222, v75, vcc
	v_cmp_lt_i32_e32 vcc, 47, v44
	s_nop 1
	v_cndmask_b32_e32 v40, v222, v40, vcc
	v_cmp_lt_i32_e32 vcc, 48, v44
	s_nop 1
	v_cndmask_b32_e32 v41, v222, v41, vcc
	v_cmp_lt_i32_e32 vcc, 49, v44
	s_nop 1
	v_cndmask_b32_e32 v42, v222, v42, vcc
	v_cmp_lt_i32_e32 vcc, 50, v44
	s_nop 1
	v_cndmask_b32_e32 v43, v222, v43, vcc

; #define LAS __attribute__((address_space(3)))
; #define MFMA16(a, b, c) __builtin_amdgcn_mfma_f32_16x16x32_bf16((a), (b), (c), 0, 0, 0)
; __device__ __forceinline__ void sel_group(const LAS bf16_t* Kt, const LAS bf16_t* Vt, LAS float* S, const bf16x8 qB0, const bf16x8 qB1, int jc, int rc, bool valid, bool masked, int tw64, int lr, int q) {
;     LAS float* Srow = S + (jc * 3 + rc) * 68;
;     const float mref = Srow[65]; const bool st = Srow[66] != 0.f;
;     f32x4 acc[4];
; #pragma unroll
;     for (int dt = 0; dt < 4; ++dt) acc[dt] = *(const LAS f32x4*)(Srow + 16 * dt + 4 * q);
;     float lc = Srow[64];
;     const float nm = valid ? -mref : -1e30f;
;     const f32x4 c0 = (f32x4){nm, nm, nm, nm};
;     const LAS bf16_t* kbase = Kt + lr * 72 + 8 * q;
;     f32x4 s[4];
;     {
;         bf16x8 kf[2][2];
;         kf[0][0] = *(const LAS bf16x8*)(kbase); kf[0][1] = *(const LAS bf16x8*)(kbase + 32);
; #pragma unroll
;         for (int mt = 0; mt < 4; ++mt) {
;             if (mt < 3) { kf[(mt + 1) & 1][0] = *(const LAS bf16x8*)(kbase + 16 * (mt + 1) * 72); kf[(mt + 1) & 1][1] = *(const LAS bf16x8*)(kbase + 16 * (mt + 1) * 72 + 32); }
;             __builtin_amdgcn_sched_barrier(0);
;             __builtin_amdgcn_s_setprio(1); s[mt] = MFMA16(kf[mt & 1][0], qB0, c0); s[mt] = MFMA16(kf[mt & 1][1], qB1, s[mt]); __builtin_amdgcn_s_setprio(0);
;             __builtin_amdgcn_sched_barrier(0);
;         }
;     }
;     if (masked) {
;         const int hq = tw64 + jc - 4 * q;
; #pragma unroll
;         for (int mt = 0; mt < 4; ++mt)
; #pragma unroll
;             for (int i = 0; i < 4; ++i) s[mt][i] = ((16 * mt + i) <= hq) ? s[mt][i] : -1e30f;
.LBB0_1092:
	s_cmp_lt_u32 s10, 11
	s_cbranch_scc1 .LBB0_1057
	s_nop 0
	v_mad_u64_u32 v[40:41], s[4:5], v116, 3, v[96:97]
	v_mul_lo_u32 v40, v40, s36
	v_add_u32_e32 v71, s49, v40
	v_add_u32_e32 v40, v71, v97
	ds_read_b96 v[68:70], v71 offset:46336
	ds_read_b128 v[56:59], v117
	ds_read_b128 v[60:63], v117 offset:64
	ds_read_b128 v[64:67], v117 offset:2304
	ds_read_b128 v[72:75], v117 offset:2368
	ds_read_b128 v[80:83], v117 offset:4608
	ds_read_b128 v[118:121], v117 offset:4672
	ds_read_b128 v[174:177], v117 offset:6912
	ds_read_b128 v[122:125], v117 offset:6976
	ds_read_b128 v[52:55], v40 offset:46080
	ds_read_b128 v[48:51], v40 offset:46144
	ds_read_b128 v[44:47], v40 offset:46208
	ds_read_b128 v[40:43], v40 offset:46272
	s_waitcnt lgkmcnt(12)
	v_cndmask_b32_e64 v76, v222, -v69, s[70:71]
	v_mov_b32_e32 v77, v76
	v_mov_b32_e32 v78, v76
	v_mov_b32_e32 v79, v76
	s_setprio 1
	s_waitcnt lgkmcnt(11)
	v_mfma_f32_16x16x32_bf16 v[56:59], v[56:59], v[32:35], v[76:79]
	s_waitcnt lgkmcnt(10)
	v_mfma_f32_16x16x32_bf16 v[56:59], v[60:63], v[36:39], v[56:59]
	s_waitcnt lgkmcnt(9)
	v_mfma_f32_16x16x32_bf16 v[60:63], v[64:67], v[32:35], v[76:79]
	s_waitcnt lgkmcnt(8)
	v_mfma_f32_16x16x32_bf16 v[60:63], v[72:75], v[36:39], v[60:63]
	s_waitcnt lgkmcnt(7)
	v_mfma_f32_16x16x32_bf16 v[64:67], v[80:83], v[32:35], v[76:79]
	s_waitcnt lgkmcnt(6)
	v_mfma_f32_16x16x32_bf16 v[64:67], v[118:121], v[36:39], v[64:67]
	s_waitcnt lgkmcnt(5)
	v_mfma_f32_16x16x32_bf16 v[32:35], v[174:177], v[32:35], v[76:79]
	s_waitcnt lgkmcnt(4)
	v_mfma_f32_16x16x32_bf16 v[32:35], v[122:125], v[36:39], v[32:35]
	s_setprio 0
	s_and_b64 vcc, exec, s[72:73]
	s_cbranch_vccnz .LBB0_1095
	v_add_u32_e32 v36, v116, v111
	v_cmp_lt_i32_e32 vcc, -1, v36
	s_nop 1
	v_cndmask_b32_e32 v56, v222, v56, vcc
	v_cmp_lt_i32_e32 vcc, 0, v36
	s_nop 1
	v_cndmask_b32_e32 v57, v222, v57, vcc
	v_cmp_lt_i32_e32 vcc, 1, v36
	s_nop 1
	v_cndmask_b32_e32 v58, v222, v58, vcc
	v_cmp_lt_i32_e32 vcc, 2, v36
	s_nop 1
	v_cndmask_b32_e32 v59, v222, v59, vcc
	v_cmp_lt_i32_e32 vcc, 15, v36
	s_nop 1
	v_cndmask_b32_e32 v60, v222, v60, vcc
	v_cmp_lt_i32_e32 vcc, 16, v36
	s_nop 1
	v_cndmask_b32_e32 v61, v222, v61, vcc
	v_cmp_lt_i32_e32 vcc, 17, v36
	s_nop 1
	v_cndmask_b32_e32 v62, v222, v62, vcc
	v_cmp_lt_i32_e32 vcc, 18, v36
	s_nop 1
	v_cndmask_b32_e32 v63, v222, v63, vcc
	v_cmp_lt_i32_e32 vcc, 31, v36
	s_nop 1
	v_cndmask_b32_e32 v64, v222, v64, vcc
	v_cmp_lt_i32_e32 vcc, 32, v36
	s_nop 1
	v_cndmask_b32_e32 v65, v222, v65, vcc
	v_cmp_lt_i32_e32 vcc, 33, v36
	s_nop 1
	v_cndmask_b32_e32 v66, v222, v66, vcc
	v_cmp_lt_i32_e32 vcc, 34, v36
	s_nop 1
	v_cndmask_b32_e32 v67, v222, v67, vcc
	v_cmp_lt_i32_e32 vcc, 47, v36
	s_nop 1
	v_cndmask_b32_e32 v32, v222, v32, vcc
	v_cmp_lt_i32_e32 vcc, 48, v36
	s_nop 1
	v_cndmask_b32_e32 v33, v222, v33, vcc
	v_cmp_lt_i32_e32 vcc, 49, v36
	s_nop 1
	v_cndmask_b32_e32 v34, v222, v34, vcc
	v_cmp_lt_i32_e32 vcc, 50, v36
	s_nop 1
	v_cndmask_b32_e32 v35, v222, v35, vcc
